# counted per-MFMA lgkmcnt waits in the PV section and one-step-ahead K fragment prefetch (alternating fragment buffers) in the QK section of the GQA and MLA attention loops
# speedup vs baseline: 1.1362x; 1.0277x over previous
.LBB0_119:
	s_mov_b32 s38, s10
	s_ashr_i32 s9, s8, 31
	s_lshl_b32 s11, s20, 9
	s_add_u32 s12, s14, s11
	s_addc_u32 s13, s15, 0
	s_ashr_i32 s11, s10, 31
	v_lshl_add_u64 v[2:3], s[10:11], 0, v[170:171]
	v_lshl_add_u64 v[6:7], v[174:175], 0, s[10:11]
	v_lshlrev_b64 v[22:23], 12, v[2:3]
	v_lshlrev_b64 v[6:7], 12, v[6:7]
	v_lshl_add_u64 v[10:11], s[10:11], 0, v[172:173]
	v_lshl_add_u64 v[2:3], s[12:13], 0, v[22:23]
	v_mov_b32_e32 v189, v1
	v_lshl_add_u64 v[6:7], s[12:13], 0, v[6:7]
	v_lshlrev_b64 v[24:25], 12, v[10:11]
	v_lshl_add_u64 v[14:15], v[2:3], 0, v[188:189]
	v_lshl_add_u64 v[18:19], v[6:7], 0, v[188:189]
	v_lshl_add_u64 v[10:11], v[176:177], 0, v[24:25]
	global_load_dwordx4 v[2:5], v[14:15], off
	global_load_dwordx4 v[6:9], v[18:19], off
	s_nop 0
	global_load_dwordx4 v[10:13], v[10:11], off
	s_nop 0
	global_load_dwordx4 v[14:17], v[14:15], off offset:256
	s_nop 0
	global_load_dwordx4 v[18:21], v[18:19], off offset:256
	v_add_u32_e32 v26, 16, v198
	s_waitcnt vmcnt(0)
	s_and_b32 s22, s18, 7
	v_lshl_or_b32 v22, s22, 9, v22
	s_lshl_b32 s10, s21, 18
	v_lshl_add_u64 v[192:193], v[184:185], 0, v[24:25]
	v_lshl_add_u64 v[194:195], v[186:187], 0, v[22:23]
	s_add_u32 s21, s10, 0x40000
	s_mov_b32 s22, 0
	v_mov_b32_e32 v234, 0
	v_mov_b32_e32 v189, 0xf149f2ca
	s_mov_b64 s[10:11], 0
	s_waitcnt vmcnt(0)
	ds_write_b128 v26, v[14:17]
	v_add_u32_e32 v14, 16, v199
	s_waitcnt vmcnt(0)
	ds_write_b128 v14, v[18:21]
	v_add_u32_e32 v14, 16, v200
	ds_write_b128 v14, v[2:5] offset:32768
	ds_write_b128 v14, v[6:9] offset:45056
	v_add_u32_e32 v2, 16, v201
	v_mov_b32_e32 v16, v1
	v_mov_b32_e32 v17, v1
	ds_write_b128 v2, v[10:13] offset:32768
	v_mov_b32_e32 v2, v1
	v_mov_b32_e32 v3, v1
	v_mov_b32_e32 v4, v1
	v_mov_b32_e32 v5, v1
	v_mov_b32_e32 v6, v1
	v_mov_b32_e32 v7, v1
	v_mov_b32_e32 v8, v1
	v_mov_b32_e32 v9, v1
	v_mov_b32_e32 v10, v1
	v_mov_b32_e32 v11, v1
	v_mov_b32_e32 v12, v1
	v_mov_b32_e32 v13, v1
	v_mov_b32_e32 v14, v1
	v_mov_b32_e32 v15, v1
	v_mov_b64_e32 v[32:33], v[16:17]
	v_mov_b64_e32 v[48:49], v[16:17]
	v_mov_b64_e32 v[64:65], v[16:17]
	v_mov_b64_e32 v[30:31], v[14:15]
	v_mov_b64_e32 v[28:29], v[12:13]
	v_mov_b64_e32 v[26:27], v[10:11]
	v_mov_b64_e32 v[24:25], v[8:9]
	v_mov_b64_e32 v[22:23], v[6:7]
	v_mov_b64_e32 v[20:21], v[4:5]
	v_mov_b64_e32 v[18:19], v[2:3]
	v_mov_b64_e32 v[46:47], v[14:15]
	v_mov_b64_e32 v[44:45], v[12:13]
	v_mov_b64_e32 v[42:43], v[10:11]
	v_mov_b64_e32 v[40:41], v[8:9]
	v_mov_b64_e32 v[38:39], v[6:7]
	v_mov_b64_e32 v[36:37], v[4:5]
	v_mov_b64_e32 v[34:35], v[2:3]
	v_mov_b64_e32 v[62:63], v[14:15]
	v_mov_b64_e32 v[60:61], v[12:13]
	v_mov_b64_e32 v[58:59], v[10:11]
	v_mov_b64_e32 v[56:57], v[8:9]
	v_mov_b64_e32 v[54:55], v[6:7]
	v_mov_b64_e32 v[52:53], v[4:5]
	v_mov_b64_e32 v[50:51], v[2:3]
	s_waitcnt lgkmcnt(0)
	s_barrier
	s_lshl_b32 s12, s20, 9
	s_add_i32 s12, s12, 0x8400000
	v_and_b32_e32 v66, 63, v178
	v_lshrrev_b32_e32 v67, 6, v178
	v_mul_u32_u24_e32 v68, 0xc0, v67
	v_add_u32_e32 v68, v68, v66
	v_mul_u32_u24_e32 v70, 0xaab, v68
	v_lshrrev_b32_e32 v70, 16, v70
	v_mul_u32_u24_e32 v71, 24, v70
	v_sub_u32_e32 v71, v68, v71
	v_and_b32_e32 v72, 15, v70
	v_xor_b32_e32 v72, v71, v72
	v_lshlrev_b32_e32 v72, 4, v72
	v_add_u32_e32 v72, s12, v72
	v_add_u32_e32 v73, -16, v71
	v_and_b32_e32 v74, 7, v70
	v_xor_b32_e32 v73, v73, v74
	v_lshlrev_b32_e32 v73, 4, v73
	v_add_u32_e32 v73, 0x600, v73
	v_cmp_gt_u32_e32 vcc, 16, v71
	s_nop 1
	v_cndmask_b32_e32 v72, v73, v72, vcc
	v_lshl_add_u32 v247, v70, 12, v72
	v_add_u32_e32 v68, 64, v68
	v_mul_u32_u24_e32 v70, 0xaab, v68
	v_lshrrev_b32_e32 v70, 16, v70
	v_mul_u32_u24_e32 v71, 24, v70
	v_sub_u32_e32 v71, v68, v71
	v_and_b32_e32 v72, 15, v70
	v_xor_b32_e32 v72, v71, v72
	v_lshlrev_b32_e32 v72, 4, v72
	v_add_u32_e32 v72, s12, v72
	v_add_u32_e32 v73, -16, v71
	v_and_b32_e32 v74, 7, v70
	v_xor_b32_e32 v73, v73, v74
	v_lshlrev_b32_e32 v73, 4, v73
	v_add_u32_e32 v73, 0x600, v73
	v_cmp_gt_u32_e32 vcc, 16, v71
	s_nop 1
	v_cndmask_b32_e32 v72, v73, v72, vcc
	v_lshl_add_u32 v248, v70, 12, v72
	v_add_u32_e32 v68, 64, v68
	v_mul_u32_u24_e32 v70, 0xaab, v68
	v_lshrrev_b32_e32 v70, 16, v70
	v_mul_u32_u24_e32 v71, 24, v70
	v_sub_u32_e32 v71, v68, v71
	v_and_b32_e32 v72, 15, v70
	v_xor_b32_e32 v72, v71, v72
	v_lshlrev_b32_e32 v72, 4, v72
	v_add_u32_e32 v72, s12, v72
	v_add_u32_e32 v73, -16, v71
	v_and_b32_e32 v74, 7, v70
	v_xor_b32_e32 v73, v73, v74
	v_lshlrev_b32_e32 v73, 4, v73
	v_add_u32_e32 v73, 0x600, v73
	v_cmp_gt_u32_e32 vcc, 16, v71
	s_nop 1
	v_cndmask_b32_e32 v72, v73, v72, vcc
	v_lshl_add_u32 v249, v70, 12, v72
	v_and_b32_e32 v70, 31, v66
	v_lshrrev_b32_e32 v70, 2, v70
	v_lshl_add_u32 v70, v67, 3, v70
	v_lshrrev_b32_e32 v71, 5, v66
	v_lshlrev_b32_e32 v71, 6, v71
	v_and_b32_e32 v72, 3, v66
	v_lshlrev_b32_e32 v72, 4, v72
	v_add3_u32 v71, v71, v72, s12
	v_add_u32_e32 v71, 0x100, v71
	v_lshl_add_u32 v250, v70, 12, v71
	v_add_u32_e32 v251, 0x80, v250
	s_add_i32 s24, s38, 64
	s_lshl_b32 s24, s24, 12
	s_add_u32 s24, s24, 0x4600000
	s_add_u32 s24, s98, s24
	s_addc_u32 s25, s99, 0
	v_readlane_b32 s26, v254, 10
	s_nop 3
	s_lshr_b32 s36, s26, 6
	s_lshl_b32 s26, s26, 5
	s_add_i32 s26, s26, 16
	s_mul_i32 s36, s36, 0xc00
	s_add_i32 s36, s36, 0x8010
	s_movk_i32 s12, 0x2000
	v_add3_u32 v146, v203, v220, s12
	v_add3_u32 v147, v203, v221, s12
	v_add3_u32 v163, v203, v222, s12
	v_add3_u32 v164, v203, v223, s12
	v_add3_u32 v165, v203, v224, s12
	v_add3_u32 v156, v203, v225, s12
	v_add3_u32 v157, v203, v226, s12
	v_add3_u32 v158, v203, v227, s12
	v_add3_u32 v159, v203, v228, s12
	v_add3_u32 v160, v203, v229, s12
	v_add3_u32 v161, v203, v230, s12
	v_add3_u32 v162, v203, v231, s12
	s_branch .Lmu_b120
.Lmu_a120:
	ds_read_b128 v[66:69], v146 offset:49152
	ds_read_b128 v[70:73], v146 offset:61440
	ds_read_b128 v[236:239], v147 offset:49152
	ds_read_b128 v[240:243], v147 offset:61440
	s_waitcnt lgkmcnt(3)
	v_mfma_f32_32x32x16_bf16 v[82:97], v[66:69], v[134:137], 0
	s_waitcnt lgkmcnt(2)
	v_mfma_f32_32x32x16_bf16 v[66:81], v[70:73], v[134:137], 0
	ds_read_b128 v[148:151], v163 offset:49152
	ds_read_b128 v[152:155], v163 offset:61440
	s_waitcnt lgkmcnt(3)
	v_mfma_f32_32x32x16_bf16 v[82:97], v[236:239], v[130:133], v[82:97]
	s_waitcnt lgkmcnt(2)
	v_mfma_f32_32x32x16_bf16 v[66:81], v[240:243], v[130:133], v[66:81]
	ds_read_b128 v[236:239], v164 offset:49152
	ds_read_b128 v[240:243], v164 offset:61440
	s_waitcnt lgkmcnt(3)
	v_mfma_f32_32x32x16_bf16 v[82:97], v[148:151], v[126:129], v[82:97]
	s_waitcnt lgkmcnt(2)
	v_mfma_f32_32x32x16_bf16 v[66:81], v[152:155], v[126:129], v[66:81]
	ds_read_b128 v[148:151], v165 offset:49152
	ds_read_b128 v[152:155], v165 offset:61440
	s_waitcnt lgkmcnt(3)
	v_mfma_f32_32x32x16_bf16 v[82:97], v[236:239], v[122:125], v[82:97]
	s_waitcnt lgkmcnt(2)
	v_mfma_f32_32x32x16_bf16 v[66:81], v[240:243], v[122:125], v[66:81]
	ds_read_b128 v[236:239], v156 offset:49152
	ds_read_b128 v[240:243], v156 offset:61440
	s_waitcnt lgkmcnt(3)
	v_mfma_f32_32x32x16_bf16 v[82:97], v[148:151], v[118:121], v[82:97]
	s_waitcnt lgkmcnt(2)
	v_mfma_f32_32x32x16_bf16 v[66:81], v[152:155], v[118:121], v[66:81]
	ds_read_b128 v[148:151], v157 offset:49152
	ds_read_b128 v[152:155], v157 offset:61440
	s_waitcnt lgkmcnt(3)
	v_mfma_f32_32x32x16_bf16 v[82:97], v[236:239], v[114:117], v[82:97]
	s_waitcnt lgkmcnt(2)
	v_mfma_f32_32x32x16_bf16 v[66:81], v[240:243], v[114:117], v[66:81]
	ds_read_b128 v[236:239], v158 offset:49152
	ds_read_b128 v[240:243], v158 offset:61440
	s_waitcnt lgkmcnt(3)
	v_mfma_f32_32x32x16_bf16 v[82:97], v[148:151], v[110:113], v[82:97]
	s_waitcnt lgkmcnt(2)
	v_mfma_f32_32x32x16_bf16 v[66:81], v[152:155], v[110:113], v[66:81]
	ds_read_b128 v[148:151], v159 offset:49152
	ds_read_b128 v[152:155], v159 offset:61440
	s_waitcnt lgkmcnt(3)
	v_mfma_f32_32x32x16_bf16 v[82:97], v[236:239], v[106:109], v[82:97]
	s_waitcnt lgkmcnt(2)
	v_mfma_f32_32x32x16_bf16 v[66:81], v[240:243], v[106:109], v[66:81]
	ds_read_b128 v[236:239], v160 offset:49152
	ds_read_b128 v[240:243], v160 offset:61440
	s_waitcnt lgkmcnt(3)
	v_mfma_f32_32x32x16_bf16 v[82:97], v[148:151], v[102:105], v[82:97]
	s_waitcnt lgkmcnt(2)
	v_mfma_f32_32x32x16_bf16 v[66:81], v[152:155], v[102:105], v[66:81]
	ds_read_b128 v[148:151], v161 offset:49152
	ds_read_b128 v[152:155], v161 offset:61440
	s_waitcnt lgkmcnt(3)
	v_mfma_f32_32x32x16_bf16 v[82:97], v[236:239], v[98:101], v[82:97]
	s_waitcnt lgkmcnt(2)
	v_mfma_f32_32x32x16_bf16 v[66:81], v[240:243], v[98:101], v[66:81]
	ds_read_b128 v[236:239], v162 offset:49152
	ds_read_b128 v[240:243], v162 offset:61440
	s_waitcnt lgkmcnt(3)
	v_mfma_f32_32x32x16_bf16 v[82:97], v[148:151], v[138:141], v[82:97]
	s_waitcnt lgkmcnt(2)
	v_mfma_f32_32x32x16_bf16 v[66:81], v[152:155], v[138:141], v[66:81]
	s_waitcnt lgkmcnt(1)
	v_mfma_f32_32x32x16_bf16 v[82:97], v[236:239], v[142:145], v[82:97]
	s_waitcnt lgkmcnt(0)
	v_mfma_f32_32x32x16_bf16 v[66:81], v[240:243], v[142:145], v[66:81]
	s_mov_b32 m0, s26
	s_nop 0
	global_load_lds_dwordx4 v250, s[24:25]
	s_add_i32 m0, s26, 0x400
	s_nop 0
	global_load_lds_dwordx4 v251, s[24:25]
	s_mov_b32 m0, s36
	s_nop 0
	global_load_lds_dwordx4 v247, s[24:25]
	s_add_i32 m0, s36, 0x400
	s_nop 0
	global_load_lds_dwordx4 v248, s[24:25]
	s_add_i32 m0, s36, 0x800
	s_nop 0
	global_load_lds_dwordx4 v249, s[24:25]
	s_add_u32 s24, s24, 0x40000
	s_addc_u32 s25, s25, 0
	s_nop 1
	v_max_f32_e32 v191, v83, v83
	v_max_f32_e32 v235, v82, v82
	v_max_f32_e32 v191, v235, v191
	v_max3_f32 v191, v191, v84, v85
	v_max3_f32 v191, v191, v86, v87
	v_max3_f32 v191, v191, v88, v89
	v_max3_f32 v191, v191, v90, v91
	v_max3_f32 v191, v191, v92, v93
	v_max3_f32 v191, v191, v94, v95
	v_max3_f32 v191, v191, v96, v97
	v_max3_f32 v191, v191, v66, v67
	v_max3_f32 v191, v191, v68, v69
	v_max3_f32 v191, v191, v70, v71
	v_max3_f32 v191, v191, v72, v73
	v_max3_f32 v191, v191, v74, v75
	v_max3_f32 v191, v191, v76, v77
	v_max3_f32 v191, v191, v78, v79
	v_max3_f32 v191, v191, v80, v81
	v_mov_b32_e32 v235, v191
	s_nop 1
	v_permlane32_swap_b32_e32 v191, v235
	v_max_f32_e32 v235, v235, v235
	v_max_f32_e32 v191, v191, v191
	v_max_f32_e32 v191, v191, v235
	v_sub_f32_e32 v235, v191, v189
	v_cmp_ge_f32_e32 vcc, s56, v235
	s_cmp_eq_u64 vcc, exec
	v_max_f32_e32 v235, v189, v189
	s_cselect_b64 vcc, -1, 0
	v_max_f32_e32 v191, v235, v191
	v_sub_f32_e32 v235, v189, v191
	v_cndmask_b32_e32 v189, v191, v189, vcc
	v_mul_f32_e32 v191, 0xbdd53b94, v189
	v_fmamk_f32 v82, v82, 0x3dd53b94, v191
	v_fmamk_f32 v83, v83, 0x3dd53b94, v191
	v_fmamk_f32 v84, v84, 0x3dd53b94, v191
	v_fmamk_f32 v85, v85, 0x3dd53b94, v191
	v_fmamk_f32 v86, v86, 0x3dd53b94, v191
	v_fmamk_f32 v87, v87, 0x3dd53b94, v191
	v_fmamk_f32 v88, v88, 0x3dd53b94, v191
	v_fmamk_f32 v89, v89, 0x3dd53b94, v191
	v_fmamk_f32 v90, v90, 0x3dd53b94, v191
	v_fmamk_f32 v91, v91, 0x3dd53b94, v191
	v_fmamk_f32 v92, v92, 0x3dd53b94, v191
	v_fmamk_f32 v93, v93, 0x3dd53b94, v191
	v_fmamk_f32 v94, v94, 0x3dd53b94, v191
	v_fmamk_f32 v95, v95, 0x3dd53b94, v191
	v_fmamk_f32 v96, v96, 0x3dd53b94, v191
	v_fmamk_f32 v97, v97, 0x3dd53b94, v191
	v_fmamk_f32 v66, v66, 0x3dd53b94, v191
	v_fmamk_f32 v67, v67, 0x3dd53b94, v191
	v_fmamk_f32 v68, v68, 0x3dd53b94, v191
	v_fmamk_f32 v69, v69, 0x3dd53b94, v191
	v_fmamk_f32 v70, v70, 0x3dd53b94, v191
	v_fmamk_f32 v71, v71, 0x3dd53b94, v191
	v_fmamk_f32 v72, v72, 0x3dd53b94, v191
	v_fmamk_f32 v73, v73, 0x3dd53b94, v191
	v_fmamk_f32 v74, v74, 0x3dd53b94, v191
	v_fmamk_f32 v75, v75, 0x3dd53b94, v191
	v_fmamk_f32 v76, v76, 0x3dd53b94, v191
	v_fmamk_f32 v77, v77, 0x3dd53b94, v191
	v_fmamk_f32 v78, v78, 0x3dd53b94, v191
	v_fmamk_f32 v79, v79, 0x3dd53b94, v191
	v_fmamk_f32 v80, v80, 0x3dd53b94, v191
	v_fmac_f32_e32 v191, 0x3dd53b94, v81
	v_exp_f32_e32 v81, v82
	v_exp_f32_e32 v236, v83
	v_exp_f32_e32 v84, v84
	v_exp_f32_e32 v85, v85
	v_exp_f32_e32 v86, v86
	v_exp_f32_e32 v237, v70
	v_add_f32_e32 v70, 0, v81
	v_exp_f32_e32 v87, v87
	v_add_f32_e32 v70, v236, v70
	v_exp_f32_e32 v88, v88
	v_add_f32_e32 v70, v84, v70
	v_exp_f32_e32 v89, v89
	v_add_f32_e32 v70, v85, v70
	v_exp_f32_e32 v90, v90
	v_add_f32_e32 v70, v86, v70
	v_exp_f32_e32 v91, v91
	v_add_f32_e32 v70, v87, v70
	v_exp_f32_e32 v92, v92
	v_add_f32_e32 v70, v88, v70
	v_exp_f32_e32 v93, v93
	v_add_f32_e32 v70, v89, v70
	v_exp_f32_e32 v94, v94
	v_add_f32_e32 v70, v90, v70
	v_exp_f32_e32 v95, v95
	v_add_f32_e32 v70, v91, v70
	v_exp_f32_e32 v96, v96
	v_add_f32_e32 v70, v92, v70
	v_exp_f32_e32 v97, v97
	v_add_f32_e32 v70, v93, v70
	v_exp_f32_e32 v66, v66
	v_add_f32_e32 v70, v94, v70
	v_exp_f32_e32 v67, v67
	v_add_f32_e32 v70, v95, v70
	v_exp_f32_e32 v68, v68
	v_add_f32_e32 v70, v96, v70
	v_exp_f32_e32 v69, v69
	v_add_f32_e32 v70, v97, v70
	v_add_f32_e32 v70, v66, v70
	v_exp_f32_e32 v238, v71
	v_add_f32_e32 v70, v67, v70
	v_exp_f32_e32 v239, v72
	v_add_f32_e32 v70, v68, v70
	v_exp_f32_e32 v73, v73
	v_add_f32_e32 v70, v69, v70
	v_exp_f32_e32 v240, v74
	v_add_f32_e32 v70, v237, v70
	v_exp_f32_e32 v241, v75
	v_add_f32_e32 v70, v238, v70
	v_exp_f32_e32 v242, v76
	v_add_f32_e32 v70, v239, v70
	v_exp_f32_e32 v243, v77
	v_add_f32_e32 v70, v73, v70
	v_exp_f32_e32 v244, v78
	v_add_f32_e32 v70, v240, v70
	v_exp_f32_e32 v245, v79
	v_add_f32_e32 v70, v241, v70
	v_exp_f32_e32 v246, v80
	v_add_f32_e32 v70, v242, v70
	v_mul_f32_e32 v235, 0x3dd53b94, v235
	v_exp_f32_e32 v191, v191
	v_add_f32_e32 v70, v243, v70
	v_exp_f32_e32 v235, v235
	v_add_f32_e32 v70, v244, v70
	v_add_f32_e32 v70, v245, v70
	v_add_f32_e32 v70, v246, v70
	v_add_f32_e32 v82, v191, v70
	v_cndmask_b32_e64 v235, v235, 1.0, vcc
	v_mov_b32_e32 v83, v82
	s_nop 1
	v_permlane32_swap_b32_e32 v82, v83
	v_cmp_gt_f32_e32 vcc, 1.0, v235
	v_cvt_pk_bf16_f32 v78, v81, v236
	v_cvt_pk_bf16_f32 v79, v84, v85
	v_cvt_pk_bf16_f32 v80, v86, v87
	v_cvt_pk_bf16_f32 v81, v88, v89
	v_cvt_pk_bf16_f32 v74, v90, v91
	v_cvt_pk_bf16_f32 v75, v92, v93
	v_cvt_pk_bf16_f32 v76, v94, v95
	v_cvt_pk_bf16_f32 v77, v96, v97
	v_cvt_pk_bf16_f32 v70, v66, v67
	v_cvt_pk_bf16_f32 v71, v68, v69
	v_cvt_pk_bf16_f32 v72, v237, v238
	v_cvt_pk_bf16_f32 v73, v239, v73
	v_cvt_pk_bf16_f32 v66, v240, v241
	v_cvt_pk_bf16_f32 v67, v242, v243
	v_cvt_pk_bf16_f32 v68, v244, v245
	v_cvt_pk_bf16_f32 v69, v246, v191
	s_cbranch_vccz .Lmu_a124
	s_and_saveexec_b64 s[12:13], s[4:5]
	ds_write_b32 v232, v235 offset:128
	s_or_b64 exec, exec, s[12:13]
	s_waitcnt lgkmcnt(0)
	v_add_u32_e32 v96, v196, v202
	ds_read_b128 v[84:87], v96 offset:224
	ds_read_b128 v[88:91], v96 offset:192
	ds_read_b128 v[92:95], v96 offset:160
	ds_read_b128 v[236:239], v96 offset:128
	s_waitcnt lgkmcnt(3)
	v_pk_mul_f32 v[14:15], v[14:15], v[84:85]
	s_waitcnt lgkmcnt(2)
	v_pk_mul_f32 v[10:11], v[10:11], v[88:89]
	s_waitcnt lgkmcnt(1)
	v_pk_mul_f32 v[6:7], v[6:7], v[92:93]
	v_pk_mul_f32 v[16:17], v[16:17], v[86:87]
	v_pk_mul_f32 v[12:13], v[12:13], v[90:91]
	v_pk_mul_f32 v[8:9], v[8:9], v[94:95]
	s_waitcnt lgkmcnt(0)
	v_pk_mul_f32 v[4:5], v[4:5], v[238:239]
	v_pk_mul_f32 v[2:3], v[2:3], v[236:237]
	v_pk_mul_f32 v[30:31], v[30:31], v[84:85]
	v_pk_mul_f32 v[26:27], v[26:27], v[88:89]
	v_pk_mul_f32 v[22:23], v[22:23], v[92:93]
	v_pk_mul_f32 v[32:33], v[32:33], v[86:87]
	v_pk_mul_f32 v[28:29], v[28:29], v[90:91]
	v_pk_mul_f32 v[24:25], v[24:25], v[94:95]
	v_pk_mul_f32 v[20:21], v[20:21], v[238:239]
	v_pk_mul_f32 v[18:19], v[18:19], v[236:237]
	v_pk_mul_f32 v[46:47], v[46:47], v[84:85]
	v_pk_mul_f32 v[42:43], v[42:43], v[88:89]
	v_pk_mul_f32 v[38:39], v[38:39], v[92:93]
	v_pk_mul_f32 v[48:49], v[48:49], v[86:87]
	v_pk_mul_f32 v[44:45], v[44:45], v[90:91]
	v_pk_mul_f32 v[40:41], v[40:41], v[94:95]
	v_pk_mul_f32 v[36:37], v[36:37], v[238:239]
	v_pk_mul_f32 v[34:35], v[34:35], v[236:237]
	v_pk_mul_f32 v[62:63], v[62:63], v[84:85]
	v_pk_mul_f32 v[58:59], v[58:59], v[88:89]
	v_pk_mul_f32 v[54:55], v[54:55], v[92:93]
	v_pk_mul_f32 v[64:65], v[64:65], v[86:87]
	v_pk_mul_f32 v[60:61], v[60:61], v[90:91]
	v_pk_mul_f32 v[56:57], v[56:57], v[94:95]
	v_pk_mul_f32 v[52:53], v[52:53], v[238:239]
	v_pk_mul_f32 v[50:51], v[50:51], v[236:237]
.Lmu_a124:
	v_add_f32_e32 v191, v82, v83
	v_fmac_f32_e32 v191, v234, v235
	ds_read_b64_tr_b16 v[82:83], v233 offset:16384
	ds_read_b64_tr_b16 v[84:85], v233 offset:18432
	ds_read_b64_tr_b16 v[86:87], v233 offset:20480
	ds_read_b64_tr_b16 v[88:89], v233 offset:22528
	ds_read_b64_tr_b16 v[90:91], v233 offset:24576
	ds_read_b64_tr_b16 v[92:93], v233 offset:26624
	ds_read_b64_tr_b16 v[94:95], v233 offset:28672
	ds_read_b64_tr_b16 v[96:97], v233 offset:30720
	s_nop 0
	s_waitcnt lgkmcnt(6)
	v_mfma_f32_32x32x16_bf16 v[2:17], v[78:81], v[82:85], v[2:17]
	ds_read_b64_tr_b16 v[82:83], v233 offset:16896
	ds_read_b64_tr_b16 v[84:85], v233 offset:18944
	s_waitcnt lgkmcnt(6)
	v_mfma_f32_32x32x16_bf16 v[2:17], v[74:77], v[86:89], v[2:17]
	ds_read_b64_tr_b16 v[86:87], v233 offset:20992
	ds_read_b64_tr_b16 v[88:89], v233 offset:23040
	s_waitcnt lgkmcnt(6)
	v_mfma_f32_32x32x16_bf16 v[2:17], v[70:73], v[90:93], v[2:17]
	ds_read_b64_tr_b16 v[90:91], v233 offset:25088
	ds_read_b64_tr_b16 v[92:93], v233 offset:27136
	s_waitcnt lgkmcnt(6)
	v_mfma_f32_32x32x16_bf16 v[2:17], v[66:69], v[94:97], v[2:17]
	ds_read_b64_tr_b16 v[94:95], v233 offset:29184
	ds_read_b64_tr_b16 v[96:97], v233 offset:31232
	s_waitcnt lgkmcnt(6)
	v_mfma_f32_32x32x16_bf16 v[18:33], v[78:81], v[82:85], v[18:33]
	ds_read_b64_tr_b16 v[82:83], v233 offset:17408
	ds_read_b64_tr_b16 v[84:85], v233 offset:19456
	s_waitcnt lgkmcnt(6)
	v_mfma_f32_32x32x16_bf16 v[18:33], v[74:77], v[86:89], v[18:33]
	ds_read_b64_tr_b16 v[86:87], v233 offset:21504
	ds_read_b64_tr_b16 v[88:89], v233 offset:23552
	s_waitcnt lgkmcnt(6)
	v_mfma_f32_32x32x16_bf16 v[18:33], v[70:73], v[90:93], v[18:33]
	ds_read_b64_tr_b16 v[90:91], v233 offset:25600
	ds_read_b64_tr_b16 v[92:93], v233 offset:27648
	s_waitcnt lgkmcnt(6)
	v_mfma_f32_32x32x16_bf16 v[18:33], v[66:69], v[94:97], v[18:33]
	ds_read_b64_tr_b16 v[94:95], v233 offset:29696
	ds_read_b64_tr_b16 v[96:97], v233 offset:31744
	s_waitcnt lgkmcnt(6)
	v_mfma_f32_32x32x16_bf16 v[34:49], v[78:81], v[82:85], v[34:49]
	ds_read_b64_tr_b16 v[82:83], v233 offset:17920
	ds_read_b64_tr_b16 v[84:85], v233 offset:19968
	s_waitcnt lgkmcnt(6)
	v_mfma_f32_32x32x16_bf16 v[34:49], v[74:77], v[86:89], v[34:49]
	ds_read_b64_tr_b16 v[86:87], v233 offset:22016
	ds_read_b64_tr_b16 v[88:89], v233 offset:24064
	s_waitcnt lgkmcnt(6)
	v_mfma_f32_32x32x16_bf16 v[34:49], v[70:73], v[90:93], v[34:49]
	ds_read_b64_tr_b16 v[90:91], v233 offset:26112
	ds_read_b64_tr_b16 v[92:93], v233 offset:28160
	s_waitcnt lgkmcnt(6)
	v_mfma_f32_32x32x16_bf16 v[34:49], v[66:69], v[94:97], v[34:49]
	ds_read_b64_tr_b16 v[94:95], v233 offset:30208
	ds_read_b64_tr_b16 v[96:97], v233 offset:32256
	s_waitcnt lgkmcnt(6)
	v_mfma_f32_32x32x16_bf16 v[50:65], v[78:81], v[82:85], v[50:65]
	s_waitcnt lgkmcnt(4)
	v_mfma_f32_32x32x16_bf16 v[50:65], v[74:77], v[86:89], v[50:65]
	s_add_u32 s10, s10, 0x40000
	s_addc_u32 s11, s11, 0
	s_add_i32 s22, s22, 1
	s_cmp_eq_u32 s21, s10
	s_waitcnt lgkmcnt(2)
	v_mfma_f32_32x32x16_bf16 v[50:65], v[70:73], v[90:93], v[50:65]
	s_waitcnt vmcnt(0)
	s_barrier
	s_waitcnt lgkmcnt(0)
	v_mfma_f32_32x32x16_bf16 v[50:65], v[66:69], v[94:97], v[50:65]
	v_mov_b32_e32 v234, v191
.Lmu_b120:
	ds_read_b128 v[66:69], v146 offset:24576
	ds_read_b128 v[70:73], v146 offset:36864
	ds_read_b128 v[236:239], v147 offset:24576
	ds_read_b128 v[240:243], v147 offset:36864
	s_waitcnt lgkmcnt(3)
	v_mfma_f32_32x32x16_bf16 v[82:97], v[66:69], v[134:137], 0
	s_waitcnt lgkmcnt(2)
	v_mfma_f32_32x32x16_bf16 v[66:81], v[70:73], v[134:137], 0
	ds_read_b128 v[148:151], v163 offset:24576
	ds_read_b128 v[152:155], v163 offset:36864
	s_waitcnt lgkmcnt(3)
	v_mfma_f32_32x32x16_bf16 v[82:97], v[236:239], v[130:133], v[82:97]
	s_waitcnt lgkmcnt(2)
	v_mfma_f32_32x32x16_bf16 v[66:81], v[240:243], v[130:133], v[66:81]
	ds_read_b128 v[236:239], v164 offset:24576
	ds_read_b128 v[240:243], v164 offset:36864
	s_waitcnt lgkmcnt(3)
	v_mfma_f32_32x32x16_bf16 v[82:97], v[148:151], v[126:129], v[82:97]
	s_waitcnt lgkmcnt(2)
	v_mfma_f32_32x32x16_bf16 v[66:81], v[152:155], v[126:129], v[66:81]
	ds_read_b128 v[148:151], v165 offset:24576
	ds_read_b128 v[152:155], v165 offset:36864
	s_waitcnt lgkmcnt(3)
	v_mfma_f32_32x32x16_bf16 v[82:97], v[236:239], v[122:125], v[82:97]
	s_waitcnt lgkmcnt(2)
	v_mfma_f32_32x32x16_bf16 v[66:81], v[240:243], v[122:125], v[66:81]
	ds_read_b128 v[236:239], v156 offset:24576
	ds_read_b128 v[240:243], v156 offset:36864
	s_waitcnt lgkmcnt(3)
	v_mfma_f32_32x32x16_bf16 v[82:97], v[148:151], v[118:121], v[82:97]
	s_waitcnt lgkmcnt(2)
	v_mfma_f32_32x32x16_bf16 v[66:81], v[152:155], v[118:121], v[66:81]
	ds_read_b128 v[148:151], v157 offset:24576
	ds_read_b128 v[152:155], v157 offset:36864
	s_waitcnt lgkmcnt(3)
	v_mfma_f32_32x32x16_bf16 v[82:97], v[236:239], v[114:117], v[82:97]
	s_waitcnt lgkmcnt(2)
	v_mfma_f32_32x32x16_bf16 v[66:81], v[240:243], v[114:117], v[66:81]
	ds_read_b128 v[236:239], v158 offset:24576
	ds_read_b128 v[240:243], v158 offset:36864
	s_waitcnt lgkmcnt(3)
	v_mfma_f32_32x32x16_bf16 v[82:97], v[148:151], v[110:113], v[82:97]
	s_waitcnt lgkmcnt(2)
	v_mfma_f32_32x32x16_bf16 v[66:81], v[152:155], v[110:113], v[66:81]
	ds_read_b128 v[148:151], v159 offset:24576
	ds_read_b128 v[152:155], v159 offset:36864
	s_waitcnt lgkmcnt(3)
	v_mfma_f32_32x32x16_bf16 v[82:97], v[236:239], v[106:109], v[82:97]
	s_waitcnt lgkmcnt(2)
	v_mfma_f32_32x32x16_bf16 v[66:81], v[240:243], v[106:109], v[66:81]
	ds_read_b128 v[236:239], v160 offset:24576
	ds_read_b128 v[240:243], v160 offset:36864
	s_waitcnt lgkmcnt(3)
	v_mfma_f32_32x32x16_bf16 v[82:97], v[148:151], v[102:105], v[82:97]
	s_waitcnt lgkmcnt(2)
	v_mfma_f32_32x32x16_bf16 v[66:81], v[152:155], v[102:105], v[66:81]
	ds_read_b128 v[148:151], v161 offset:24576
	ds_read_b128 v[152:155], v161 offset:36864
	s_waitcnt lgkmcnt(3)
	v_mfma_f32_32x32x16_bf16 v[82:97], v[236:239], v[98:101], v[82:97]
	s_waitcnt lgkmcnt(2)
	v_mfma_f32_32x32x16_bf16 v[66:81], v[240:243], v[98:101], v[66:81]
	ds_read_b128 v[236:239], v162 offset:24576
	ds_read_b128 v[240:243], v162 offset:36864
	s_waitcnt lgkmcnt(3)
	v_mfma_f32_32x32x16_bf16 v[82:97], v[148:151], v[138:141], v[82:97]
	s_waitcnt lgkmcnt(2)
	v_mfma_f32_32x32x16_bf16 v[66:81], v[152:155], v[138:141], v[66:81]
	s_waitcnt lgkmcnt(1)
	v_mfma_f32_32x32x16_bf16 v[82:97], v[236:239], v[142:145], v[82:97]
	s_waitcnt lgkmcnt(0)
	v_mfma_f32_32x32x16_bf16 v[66:81], v[240:243], v[142:145], v[66:81]
	s_add_i32 m0, s26, 0x4000
	s_nop 0
	global_load_lds_dwordx4 v250, s[24:25]
	s_add_i32 m0, s26, 0x4400
	s_nop 0
	global_load_lds_dwordx4 v251, s[24:25]
	s_add_i32 m0, s36, 0x6000
	s_nop 0
	global_load_lds_dwordx4 v247, s[24:25]
	s_add_i32 m0, s36, 0x6400
	s_nop 0
	global_load_lds_dwordx4 v248, s[24:25]
	s_add_i32 m0, s36, 0x6800
	s_nop 0
	global_load_lds_dwordx4 v249, s[24:25]
	s_add_u32 s24, s24, 0x40000
	s_addc_u32 s25, s25, 0
	s_nop 1
	v_max_f32_e32 v191, v83, v83
	v_max_f32_e32 v235, v82, v82
	v_max_f32_e32 v191, v235, v191
	v_max3_f32 v191, v191, v84, v85
	v_max3_f32 v191, v191, v86, v87
	v_max3_f32 v191, v191, v88, v89
	v_max3_f32 v191, v191, v90, v91
	v_max3_f32 v191, v191, v92, v93
	v_max3_f32 v191, v191, v94, v95
	v_max3_f32 v191, v191, v96, v97
	v_max3_f32 v191, v191, v66, v67
	v_max3_f32 v191, v191, v68, v69
	v_max3_f32 v191, v191, v70, v71
	v_max3_f32 v191, v191, v72, v73
	v_max3_f32 v191, v191, v74, v75
	v_max3_f32 v191, v191, v76, v77
	v_max3_f32 v191, v191, v78, v79
	v_max3_f32 v191, v191, v80, v81
	v_mov_b32_e32 v235, v191
	s_nop 1
	v_permlane32_swap_b32_e32 v191, v235
	v_max_f32_e32 v235, v235, v235
	v_max_f32_e32 v191, v191, v191
	v_max_f32_e32 v191, v191, v235
	v_sub_f32_e32 v235, v191, v189
	v_cmp_ge_f32_e32 vcc, s56, v235
	s_cmp_eq_u64 vcc, exec
	v_max_f32_e32 v235, v189, v189
	s_cselect_b64 vcc, -1, 0
	v_max_f32_e32 v191, v235, v191
	v_sub_f32_e32 v235, v189, v191
	v_cndmask_b32_e32 v189, v191, v189, vcc
	v_mul_f32_e32 v191, 0xbdd53b94, v189
	v_fmamk_f32 v82, v82, 0x3dd53b94, v191
	v_fmamk_f32 v83, v83, 0x3dd53b94, v191
	v_fmamk_f32 v84, v84, 0x3dd53b94, v191
	v_fmamk_f32 v85, v85, 0x3dd53b94, v191
	v_fmamk_f32 v86, v86, 0x3dd53b94, v191
	v_fmamk_f32 v87, v87, 0x3dd53b94, v191
	v_fmamk_f32 v88, v88, 0x3dd53b94, v191
	v_fmamk_f32 v89, v89, 0x3dd53b94, v191
	v_fmamk_f32 v90, v90, 0x3dd53b94, v191
	v_fmamk_f32 v91, v91, 0x3dd53b94, v191
	v_fmamk_f32 v92, v92, 0x3dd53b94, v191
	v_fmamk_f32 v93, v93, 0x3dd53b94, v191
	v_fmamk_f32 v94, v94, 0x3dd53b94, v191
	v_fmamk_f32 v95, v95, 0x3dd53b94, v191
	v_fmamk_f32 v96, v96, 0x3dd53b94, v191
	v_fmamk_f32 v97, v97, 0x3dd53b94, v191
	v_fmamk_f32 v66, v66, 0x3dd53b94, v191
	v_fmamk_f32 v67, v67, 0x3dd53b94, v191
	v_fmamk_f32 v68, v68, 0x3dd53b94, v191
	v_fmamk_f32 v69, v69, 0x3dd53b94, v191
	v_fmamk_f32 v70, v70, 0x3dd53b94, v191
	v_fmamk_f32 v71, v71, 0x3dd53b94, v191
	v_fmamk_f32 v72, v72, 0x3dd53b94, v191
	v_fmamk_f32 v73, v73, 0x3dd53b94, v191
	v_fmamk_f32 v74, v74, 0x3dd53b94, v191
	v_fmamk_f32 v75, v75, 0x3dd53b94, v191
	v_fmamk_f32 v76, v76, 0x3dd53b94, v191
	v_fmamk_f32 v77, v77, 0x3dd53b94, v191
	v_fmamk_f32 v78, v78, 0x3dd53b94, v191
	v_fmamk_f32 v79, v79, 0x3dd53b94, v191
	v_fmamk_f32 v80, v80, 0x3dd53b94, v191
	v_fmac_f32_e32 v191, 0x3dd53b94, v81
	v_exp_f32_e32 v81, v82
	v_exp_f32_e32 v236, v83
	v_exp_f32_e32 v84, v84
	v_exp_f32_e32 v85, v85
	v_exp_f32_e32 v86, v86
	v_exp_f32_e32 v237, v70
	v_add_f32_e32 v70, 0, v81
	v_exp_f32_e32 v87, v87
	v_add_f32_e32 v70, v236, v70
	v_exp_f32_e32 v88, v88
	v_add_f32_e32 v70, v84, v70
	v_exp_f32_e32 v89, v89
	v_add_f32_e32 v70, v85, v70
	v_exp_f32_e32 v90, v90
	v_add_f32_e32 v70, v86, v70
	v_exp_f32_e32 v91, v91
	v_add_f32_e32 v70, v87, v70
	v_exp_f32_e32 v92, v92
	v_add_f32_e32 v70, v88, v70
	v_exp_f32_e32 v93, v93
	v_add_f32_e32 v70, v89, v70
	v_exp_f32_e32 v94, v94
	v_add_f32_e32 v70, v90, v70
	v_exp_f32_e32 v95, v95
	v_add_f32_e32 v70, v91, v70
	v_exp_f32_e32 v96, v96
	v_add_f32_e32 v70, v92, v70
	v_exp_f32_e32 v97, v97
	v_add_f32_e32 v70, v93, v70
	v_exp_f32_e32 v66, v66
	v_add_f32_e32 v70, v94, v70
	v_exp_f32_e32 v67, v67
	v_add_f32_e32 v70, v95, v70
	v_exp_f32_e32 v68, v68
	v_add_f32_e32 v70, v96, v70
	v_exp_f32_e32 v69, v69
	v_add_f32_e32 v70, v97, v70
	v_add_f32_e32 v70, v66, v70
	v_exp_f32_e32 v238, v71
	v_add_f32_e32 v70, v67, v70
	v_exp_f32_e32 v239, v72
	v_add_f32_e32 v70, v68, v70
	v_exp_f32_e32 v73, v73
	v_add_f32_e32 v70, v69, v70
	v_exp_f32_e32 v240, v74
	v_add_f32_e32 v70, v237, v70
	v_exp_f32_e32 v241, v75
	v_add_f32_e32 v70, v238, v70
	v_exp_f32_e32 v242, v76
	v_add_f32_e32 v70, v239, v70
	v_exp_f32_e32 v243, v77
	v_add_f32_e32 v70, v73, v70
	v_exp_f32_e32 v244, v78
	v_add_f32_e32 v70, v240, v70
	v_exp_f32_e32 v245, v79
	v_add_f32_e32 v70, v241, v70
	v_exp_f32_e32 v246, v80
	v_add_f32_e32 v70, v242, v70
	v_mul_f32_e32 v235, 0x3dd53b94, v235
	v_exp_f32_e32 v191, v191
	v_add_f32_e32 v70, v243, v70
	v_exp_f32_e32 v235, v235
	v_add_f32_e32 v70, v244, v70
	v_add_f32_e32 v70, v245, v70
	v_add_f32_e32 v70, v246, v70
	v_add_f32_e32 v82, v191, v70
	v_cndmask_b32_e64 v235, v235, 1.0, vcc
	v_mov_b32_e32 v83, v82
	s_nop 1
	v_permlane32_swap_b32_e32 v82, v83
	v_cmp_gt_f32_e32 vcc, 1.0, v235
	v_cvt_pk_bf16_f32 v78, v81, v236
	v_cvt_pk_bf16_f32 v79, v84, v85
	v_cvt_pk_bf16_f32 v80, v86, v87
	v_cvt_pk_bf16_f32 v81, v88, v89
	v_cvt_pk_bf16_f32 v74, v90, v91
	v_cvt_pk_bf16_f32 v75, v92, v93
	v_cvt_pk_bf16_f32 v76, v94, v95
	v_cvt_pk_bf16_f32 v77, v96, v97
	v_cvt_pk_bf16_f32 v70, v66, v67
	v_cvt_pk_bf16_f32 v71, v68, v69
	v_cvt_pk_bf16_f32 v72, v237, v238
	v_cvt_pk_bf16_f32 v73, v239, v73
	v_cvt_pk_bf16_f32 v66, v240, v241
	v_cvt_pk_bf16_f32 v67, v242, v243
	v_cvt_pk_bf16_f32 v68, v244, v245
	v_cvt_pk_bf16_f32 v69, v246, v191
	s_cbranch_vccz .Lmu_b124
	s_and_saveexec_b64 s[12:13], s[4:5]
	ds_write_b32 v232, v235 offset:128
	s_or_b64 exec, exec, s[12:13]
	s_waitcnt lgkmcnt(0)
	v_add_u32_e32 v96, v196, v202
	ds_read_b128 v[84:87], v96 offset:224
	ds_read_b128 v[88:91], v96 offset:192
	ds_read_b128 v[92:95], v96 offset:160
	ds_read_b128 v[236:239], v96 offset:128
	s_waitcnt lgkmcnt(3)
	v_pk_mul_f32 v[14:15], v[14:15], v[84:85]
	s_waitcnt lgkmcnt(2)
	v_pk_mul_f32 v[10:11], v[10:11], v[88:89]
	s_waitcnt lgkmcnt(1)
	v_pk_mul_f32 v[6:7], v[6:7], v[92:93]
	v_pk_mul_f32 v[16:17], v[16:17], v[86:87]
	v_pk_mul_f32 v[12:13], v[12:13], v[90:91]
	v_pk_mul_f32 v[8:9], v[8:9], v[94:95]
	s_waitcnt lgkmcnt(0)
	v_pk_mul_f32 v[4:5], v[4:5], v[238:239]
	v_pk_mul_f32 v[2:3], v[2:3], v[236:237]
	v_pk_mul_f32 v[30:31], v[30:31], v[84:85]
	v_pk_mul_f32 v[26:27], v[26:27], v[88:89]
	v_pk_mul_f32 v[22:23], v[22:23], v[92:93]
	v_pk_mul_f32 v[32:33], v[32:33], v[86:87]
	v_pk_mul_f32 v[28:29], v[28:29], v[90:91]
	v_pk_mul_f32 v[24:25], v[24:25], v[94:95]
	v_pk_mul_f32 v[20:21], v[20:21], v[238:239]
	v_pk_mul_f32 v[18:19], v[18:19], v[236:237]
	v_pk_mul_f32 v[46:47], v[46:47], v[84:85]
	v_pk_mul_f32 v[42:43], v[42:43], v[88:89]
	v_pk_mul_f32 v[38:39], v[38:39], v[92:93]
	v_pk_mul_f32 v[48:49], v[48:49], v[86:87]
	v_pk_mul_f32 v[44:45], v[44:45], v[90:91]
	v_pk_mul_f32 v[40:41], v[40:41], v[94:95]
	v_pk_mul_f32 v[36:37], v[36:37], v[238:239]
	v_pk_mul_f32 v[34:35], v[34:35], v[236:237]
	v_pk_mul_f32 v[62:63], v[62:63], v[84:85]
	v_pk_mul_f32 v[58:59], v[58:59], v[88:89]
	v_pk_mul_f32 v[54:55], v[54:55], v[92:93]
	v_pk_mul_f32 v[64:65], v[64:65], v[86:87]
	v_pk_mul_f32 v[60:61], v[60:61], v[90:91]
	v_pk_mul_f32 v[56:57], v[56:57], v[94:95]
	v_pk_mul_f32 v[52:53], v[52:53], v[238:239]
	v_pk_mul_f32 v[50:51], v[50:51], v[236:237]
.Lmu_b124:
	v_add_f32_e32 v191, v82, v83
	v_fmac_f32_e32 v191, v234, v235
	ds_read_b64_tr_b16 v[82:83], v233 offset:0
	ds_read_b64_tr_b16 v[84:85], v233 offset:2048
	ds_read_b64_tr_b16 v[86:87], v233 offset:4096
	ds_read_b64_tr_b16 v[88:89], v233 offset:6144
	ds_read_b64_tr_b16 v[90:91], v233 offset:8192
	ds_read_b64_tr_b16 v[92:93], v233 offset:10240
	ds_read_b64_tr_b16 v[94:95], v233 offset:12288
	ds_read_b64_tr_b16 v[96:97], v233 offset:14336
	s_nop 0
	s_waitcnt lgkmcnt(6)
	v_mfma_f32_32x32x16_bf16 v[2:17], v[78:81], v[82:85], v[2:17]
	ds_read_b64_tr_b16 v[82:83], v233 offset:512
	ds_read_b64_tr_b16 v[84:85], v233 offset:2560
	s_waitcnt lgkmcnt(6)
	v_mfma_f32_32x32x16_bf16 v[2:17], v[74:77], v[86:89], v[2:17]
	ds_read_b64_tr_b16 v[86:87], v233 offset:4608
	ds_read_b64_tr_b16 v[88:89], v233 offset:6656
	s_waitcnt lgkmcnt(6)
	v_mfma_f32_32x32x16_bf16 v[2:17], v[70:73], v[90:93], v[2:17]
	ds_read_b64_tr_b16 v[90:91], v233 offset:8704
	ds_read_b64_tr_b16 v[92:93], v233 offset:10752
	s_waitcnt lgkmcnt(6)
	v_mfma_f32_32x32x16_bf16 v[2:17], v[66:69], v[94:97], v[2:17]
	ds_read_b64_tr_b16 v[94:95], v233 offset:12800
	ds_read_b64_tr_b16 v[96:97], v233 offset:14848
	s_waitcnt lgkmcnt(6)
	v_mfma_f32_32x32x16_bf16 v[18:33], v[78:81], v[82:85], v[18:33]
	ds_read_b64_tr_b16 v[82:83], v233 offset:1024
	ds_read_b64_tr_b16 v[84:85], v233 offset:3072
	s_waitcnt lgkmcnt(6)
	v_mfma_f32_32x32x16_bf16 v[18:33], v[74:77], v[86:89], v[18:33]
	ds_read_b64_tr_b16 v[86:87], v233 offset:5120
	ds_read_b64_tr_b16 v[88:89], v233 offset:7168
	s_waitcnt lgkmcnt(6)
	v_mfma_f32_32x32x16_bf16 v[18:33], v[70:73], v[90:93], v[18:33]
	ds_read_b64_tr_b16 v[90:91], v233 offset:9216
	ds_read_b64_tr_b16 v[92:93], v233 offset:11264
	s_waitcnt lgkmcnt(6)
	v_mfma_f32_32x32x16_bf16 v[18:33], v[66:69], v[94:97], v[18:33]
	ds_read_b64_tr_b16 v[94:95], v233 offset:13312
	ds_read_b64_tr_b16 v[96:97], v233 offset:15360
	s_waitcnt lgkmcnt(6)
	v_mfma_f32_32x32x16_bf16 v[34:49], v[78:81], v[82:85], v[34:49]
	ds_read_b64_tr_b16 v[82:83], v233 offset:1536
	ds_read_b64_tr_b16 v[84:85], v233 offset:3584
	s_waitcnt lgkmcnt(6)
	v_mfma_f32_32x32x16_bf16 v[34:49], v[74:77], v[86:89], v[34:49]
	ds_read_b64_tr_b16 v[86:87], v233 offset:5632
	ds_read_b64_tr_b16 v[88:89], v233 offset:7680
	s_waitcnt lgkmcnt(6)
	v_mfma_f32_32x32x16_bf16 v[34:49], v[70:73], v[90:93], v[34:49]
	ds_read_b64_tr_b16 v[90:91], v233 offset:9728
	ds_read_b64_tr_b16 v[92:93], v233 offset:11776
	s_waitcnt lgkmcnt(6)
	v_mfma_f32_32x32x16_bf16 v[34:49], v[66:69], v[94:97], v[34:49]
	ds_read_b64_tr_b16 v[94:95], v233 offset:13824
	ds_read_b64_tr_b16 v[96:97], v233 offset:15872
	s_waitcnt lgkmcnt(6)
	v_mfma_f32_32x32x16_bf16 v[50:65], v[78:81], v[82:85], v[50:65]
	s_waitcnt lgkmcnt(4)
	v_mfma_f32_32x32x16_bf16 v[50:65], v[74:77], v[86:89], v[50:65]
	s_add_u32 s10, s10, 0x40000
	s_addc_u32 s11, s11, 0
	s_add_i32 s22, s22, 1
	s_cmp_eq_u32 s21, s10
	s_waitcnt lgkmcnt(2)
	v_mfma_f32_32x32x16_bf16 v[50:65], v[70:73], v[90:93], v[50:65]
	s_waitcnt vmcnt(0)
	s_barrier
	s_waitcnt lgkmcnt(0)
	v_mfma_f32_32x32x16_bf16 v[50:65], v[66:69], v[94:97], v[50:65]
	s_cbranch_scc1 .LBB0_126
	v_mov_b32_e32 v234, v191
	s_branch .Lmu_a120

.Lgu_a286:
	ds_read_b128 v[82:85], v162 offset:49152
	ds_read_b128 v[86:89], v162 offset:57344
	ds_read_b128 v[90:93], v163 offset:49152
	ds_read_b128 v[94:97], v163 offset:57344
	s_waitcnt lgkmcnt(3)
	v_mfma_f32_32x32x16_bf16 v[114:129], v[82:85], v[134:137], v[66:81]
	s_waitcnt lgkmcnt(2)
	v_mfma_f32_32x32x16_bf16 v[98:113], v[86:89], v[134:137], v[66:81]
	ds_read_b128 v[82:85], v164 offset:49152
	ds_read_b128 v[86:89], v164 offset:57344
	s_waitcnt lgkmcnt(3)
	v_mfma_f32_32x32x16_bf16 v[114:129], v[90:93], v[142:145], v[114:129]
	s_waitcnt lgkmcnt(2)
	v_mfma_f32_32x32x16_bf16 v[98:113], v[94:97], v[142:145], v[98:113]
	ds_read_b128 v[90:93], v165 offset:49152
	ds_read_b128 v[94:97], v165 offset:57344
	s_waitcnt lgkmcnt(3)
	v_mfma_f32_32x32x16_bf16 v[114:129], v[82:85], v[146:149], v[114:129]
	s_waitcnt lgkmcnt(2)
	v_mfma_f32_32x32x16_bf16 v[98:113], v[86:89], v[146:149], v[98:113]
	ds_read_b128 v[82:85], v166 offset:49152
	ds_read_b128 v[86:89], v166 offset:57344
	s_waitcnt lgkmcnt(3)
	v_mfma_f32_32x32x16_bf16 v[114:129], v[90:93], v[150:153], v[114:129]
	s_waitcnt lgkmcnt(2)
	v_mfma_f32_32x32x16_bf16 v[98:113], v[94:97], v[150:153], v[98:113]
	ds_read_b128 v[90:93], v167 offset:49152
	ds_read_b128 v[94:97], v167 offset:57344
	s_waitcnt lgkmcnt(3)
	v_mfma_f32_32x32x16_bf16 v[114:129], v[82:85], v[154:157], v[114:129]
	s_waitcnt lgkmcnt(2)
	v_mfma_f32_32x32x16_bf16 v[98:113], v[86:89], v[154:157], v[98:113]
	ds_read_b128 v[82:85], v168 offset:49152
	ds_read_b128 v[86:89], v168 offset:57344
	s_waitcnt lgkmcnt(3)
	v_mfma_f32_32x32x16_bf16 v[114:129], v[90:93], v[158:161], v[114:129]
	s_waitcnt lgkmcnt(2)
	v_mfma_f32_32x32x16_bf16 v[98:113], v[94:97], v[158:161], v[98:113]
	ds_read_b128 v[90:93], v169 offset:49152
	ds_read_b128 v[94:97], v169 offset:57344
	s_waitcnt lgkmcnt(3)
	v_mfma_f32_32x32x16_bf16 v[114:129], v[82:85], v[138:141], v[114:129]
	s_waitcnt lgkmcnt(2)
	v_mfma_f32_32x32x16_bf16 v[98:113], v[86:89], v[138:141], v[98:113]
	s_waitcnt lgkmcnt(1)
	v_mfma_f32_32x32x16_bf16 v[114:129], v[90:93], v[130:133], v[114:129]
	s_waitcnt lgkmcnt(0)
	v_mfma_f32_32x32x16_bf16 v[98:113], v[94:97], v[130:133], v[98:113]
	s_mov_b32 m0, s26
	s_nop 0
	global_load_lds_dwordx4 v250, s[24:25]
	s_add_i32 m0, s26, 0x400
	s_nop 0
	global_load_lds_dwordx4 v251, s[24:25]
	s_add_i32 m0, s26, 0x8000
	s_nop 0
	global_load_lds_dwordx4 v252, s[24:25]
	s_add_i32 m0, s26, 0x8400
	s_nop 0
	global_load_lds_dwordx4 v253, s[24:25]
	s_add_u32 s24, s24, 0x50000
	s_addc_u32 s25, s25, 0
	s_nop 1
	v_max_f32_e32 v82, v115, v115
	v_max_f32_e32 v83, v114, v114
	v_max_f32_e32 v82, v83, v82
	v_max3_f32 v82, v82, v116, v117
	v_max3_f32 v82, v82, v118, v119
	v_max3_f32 v82, v82, v120, v121
	v_max3_f32 v82, v82, v122, v123
	v_max3_f32 v82, v82, v124, v125
	v_max3_f32 v82, v82, v126, v127
	v_max3_f32 v82, v82, v128, v129
	v_max3_f32 v82, v82, v98, v99
	v_max3_f32 v82, v82, v100, v101
	v_max3_f32 v82, v82, v102, v103
	v_max3_f32 v82, v82, v104, v105
	v_max3_f32 v82, v82, v106, v107
	v_max3_f32 v82, v82, v108, v109
	v_max3_f32 v82, v82, v110, v111
	v_max3_f32 v82, v82, v112, v113
	v_mov_b32_e32 v83, v82
	s_nop 1
	v_permlane32_swap_b32_e32 v82, v83
	v_max_f32_e32 v83, v83, v83
	v_max_f32_e32 v82, v82, v82
	v_max_f32_e32 v82, v82, v83
	v_cmp_ge_f32_e32 vcc, s64, v82
	s_cmp_eq_u64 vcc, exec
	s_cbranch_scc0 .Lgu_a294
	v_mov_b32_e32 v195, 1.0

.Lgu_a292:
	v_add_f32_e32 v114, v114, v115
	v_fmac_f32_e32 v114, v202, v195
	ds_read_b64_tr_b16 v[116:117], v237 offset:16384
	ds_read_b64_tr_b16 v[118:119], v237 offset:18432
	ds_read_b64_tr_b16 v[120:121], v237 offset:20480
	ds_read_b64_tr_b16 v[122:123], v237 offset:22528
	ds_read_b64_tr_b16 v[124:125], v237 offset:24576
	ds_read_b64_tr_b16 v[126:127], v237 offset:26624
	ds_read_b64_tr_b16 v[238:239], v237 offset:28672
	ds_read_b64_tr_b16 v[240:241], v237 offset:30720
	s_nop 0
	s_waitcnt lgkmcnt(6)
	v_mfma_f32_32x32x16_bf16 v[2:17], v[110:113], v[116:119], v[2:17]
	ds_read_b64_tr_b16 v[116:117], v237 offset:16896
	ds_read_b64_tr_b16 v[118:119], v237 offset:18944
	s_waitcnt lgkmcnt(6)
	v_mfma_f32_32x32x16_bf16 v[2:17], v[106:109], v[120:123], v[2:17]
	ds_read_b64_tr_b16 v[120:121], v237 offset:20992
	ds_read_b64_tr_b16 v[122:123], v237 offset:23040
	s_waitcnt lgkmcnt(6)
	v_mfma_f32_32x32x16_bf16 v[2:17], v[102:105], v[124:127], v[2:17]
	ds_read_b64_tr_b16 v[124:125], v237 offset:25088
	ds_read_b64_tr_b16 v[126:127], v237 offset:27136
	s_waitcnt lgkmcnt(6)
	v_mfma_f32_32x32x16_bf16 v[2:17], v[98:101], v[238:241], v[2:17]
	ds_read_b64_tr_b16 v[238:239], v237 offset:29184
	ds_read_b64_tr_b16 v[240:241], v237 offset:31232
	s_waitcnt lgkmcnt(6)
	v_mfma_f32_32x32x16_bf16 v[18:33], v[110:113], v[116:119], v[18:33]
	ds_read_b64_tr_b16 v[116:117], v237 offset:17408
	ds_read_b64_tr_b16 v[118:119], v237 offset:19456
	s_waitcnt lgkmcnt(6)
	v_mfma_f32_32x32x16_bf16 v[18:33], v[106:109], v[120:123], v[18:33]
	ds_read_b64_tr_b16 v[120:121], v237 offset:21504
	ds_read_b64_tr_b16 v[122:123], v237 offset:23552
	s_waitcnt lgkmcnt(6)
	v_mfma_f32_32x32x16_bf16 v[18:33], v[102:105], v[124:127], v[18:33]
	ds_read_b64_tr_b16 v[124:125], v237 offset:25600
	ds_read_b64_tr_b16 v[126:127], v237 offset:27648
	s_waitcnt lgkmcnt(6)
	v_mfma_f32_32x32x16_bf16 v[18:33], v[98:101], v[238:241], v[18:33]
	ds_read_b64_tr_b16 v[238:239], v237 offset:29696
	ds_read_b64_tr_b16 v[240:241], v237 offset:31744
	s_waitcnt lgkmcnt(6)
	v_mfma_f32_32x32x16_bf16 v[34:49], v[110:113], v[116:119], v[34:49]
	ds_read_b64_tr_b16 v[116:117], v237 offset:17920
	ds_read_b64_tr_b16 v[118:119], v237 offset:19968
	s_waitcnt lgkmcnt(6)
	v_mfma_f32_32x32x16_bf16 v[34:49], v[106:109], v[120:123], v[34:49]
	ds_read_b64_tr_b16 v[120:121], v237 offset:22016
	ds_read_b64_tr_b16 v[122:123], v237 offset:24064
	s_waitcnt lgkmcnt(6)
	v_mfma_f32_32x32x16_bf16 v[34:49], v[102:105], v[124:127], v[34:49]
	ds_read_b64_tr_b16 v[124:125], v237 offset:26112
	ds_read_b64_tr_b16 v[126:127], v237 offset:28160
	s_waitcnt lgkmcnt(6)
	v_mfma_f32_32x32x16_bf16 v[34:49], v[98:101], v[238:241], v[34:49]
	ds_read_b64_tr_b16 v[238:239], v237 offset:30208
	ds_read_b64_tr_b16 v[240:241], v237 offset:32256
	s_waitcnt lgkmcnt(6)
	v_mfma_f32_32x32x16_bf16 v[50:65], v[110:113], v[116:119], v[50:65]
	s_add_i32 s14, s14, 1
	s_cmp_eq_u32 s23, s14
	s_waitcnt lgkmcnt(4)
	v_mfma_f32_32x32x16_bf16 v[50:65], v[106:109], v[120:123], v[50:65]
	s_waitcnt vmcnt(0)
	s_waitcnt lgkmcnt(2)
	v_mfma_f32_32x32x16_bf16 v[50:65], v[102:105], v[124:127], v[50:65]
	s_barrier
	s_waitcnt lgkmcnt(0)
	v_mfma_f32_32x32x16_bf16 v[50:65], v[98:101], v[238:241], v[50:65]
	v_mov_b32_e32 v202, v114
.Lgu_b286:
	ds_read_b128 v[82:85], v162 offset:32768
	ds_read_b128 v[86:89], v162 offset:40960
	ds_read_b128 v[90:93], v163 offset:32768
	ds_read_b128 v[94:97], v163 offset:40960
	s_waitcnt lgkmcnt(3)
	v_mfma_f32_32x32x16_bf16 v[114:129], v[82:85], v[134:137], v[66:81]
	s_waitcnt lgkmcnt(2)
	v_mfma_f32_32x32x16_bf16 v[98:113], v[86:89], v[134:137], v[66:81]
	ds_read_b128 v[82:85], v164 offset:32768
	ds_read_b128 v[86:89], v164 offset:40960
	s_waitcnt lgkmcnt(3)
	v_mfma_f32_32x32x16_bf16 v[114:129], v[90:93], v[142:145], v[114:129]
	s_waitcnt lgkmcnt(2)
	v_mfma_f32_32x32x16_bf16 v[98:113], v[94:97], v[142:145], v[98:113]
	ds_read_b128 v[90:93], v165 offset:32768
	ds_read_b128 v[94:97], v165 offset:40960
	s_waitcnt lgkmcnt(3)
	v_mfma_f32_32x32x16_bf16 v[114:129], v[82:85], v[146:149], v[114:129]
	s_waitcnt lgkmcnt(2)
	v_mfma_f32_32x32x16_bf16 v[98:113], v[86:89], v[146:149], v[98:113]
	ds_read_b128 v[82:85], v166 offset:32768
	ds_read_b128 v[86:89], v166 offset:40960
	s_waitcnt lgkmcnt(3)
	v_mfma_f32_32x32x16_bf16 v[114:129], v[90:93], v[150:153], v[114:129]
	s_waitcnt lgkmcnt(2)
	v_mfma_f32_32x32x16_bf16 v[98:113], v[94:97], v[150:153], v[98:113]
	ds_read_b128 v[90:93], v167 offset:32768
	ds_read_b128 v[94:97], v167 offset:40960
	s_waitcnt lgkmcnt(3)
	v_mfma_f32_32x32x16_bf16 v[114:129], v[82:85], v[154:157], v[114:129]
	s_waitcnt lgkmcnt(2)
	v_mfma_f32_32x32x16_bf16 v[98:113], v[86:89], v[154:157], v[98:113]
	ds_read_b128 v[82:85], v168 offset:32768
	ds_read_b128 v[86:89], v168 offset:40960
	s_waitcnt lgkmcnt(3)
	v_mfma_f32_32x32x16_bf16 v[114:129], v[90:93], v[158:161], v[114:129]
	s_waitcnt lgkmcnt(2)
	v_mfma_f32_32x32x16_bf16 v[98:113], v[94:97], v[158:161], v[98:113]
	ds_read_b128 v[90:93], v169 offset:32768
	ds_read_b128 v[94:97], v169 offset:40960
	s_waitcnt lgkmcnt(3)
	v_mfma_f32_32x32x16_bf16 v[114:129], v[82:85], v[138:141], v[114:129]
	s_waitcnt lgkmcnt(2)
	v_mfma_f32_32x32x16_bf16 v[98:113], v[86:89], v[138:141], v[98:113]
	s_waitcnt lgkmcnt(1)
	v_mfma_f32_32x32x16_bf16 v[114:129], v[90:93], v[130:133], v[114:129]
	s_waitcnt lgkmcnt(0)
	v_mfma_f32_32x32x16_bf16 v[98:113], v[94:97], v[130:133], v[98:113]
	s_add_i32 m0, s26, 0x4000
	s_nop 0
	global_load_lds_dwordx4 v250, s[24:25]
	s_add_i32 m0, s26, 0x4400
	s_nop 0
	global_load_lds_dwordx4 v251, s[24:25]
	s_add_i32 m0, s26, 0xc000
	s_nop 0
	global_load_lds_dwordx4 v252, s[24:25]
	s_add_i32 m0, s26, 0xc400
	s_nop 0
	global_load_lds_dwordx4 v253, s[24:25]
	s_add_u32 s24, s24, 0x50000
	s_addc_u32 s25, s25, 0
	s_nop 1
	v_max_f32_e32 v82, v115, v115
	v_max_f32_e32 v83, v114, v114
	v_max_f32_e32 v82, v83, v82
	v_max3_f32 v82, v82, v116, v117
	v_max3_f32 v82, v82, v118, v119
	v_max3_f32 v82, v82, v120, v121
	v_max3_f32 v82, v82, v122, v123
	v_max3_f32 v82, v82, v124, v125
	v_max3_f32 v82, v82, v126, v127
	v_max3_f32 v82, v82, v128, v129
	v_max3_f32 v82, v82, v98, v99
	v_max3_f32 v82, v82, v100, v101
	v_max3_f32 v82, v82, v102, v103
	v_max3_f32 v82, v82, v104, v105
	v_max3_f32 v82, v82, v106, v107
	v_max3_f32 v82, v82, v108, v109
	v_max3_f32 v82, v82, v110, v111
	v_max3_f32 v82, v82, v112, v113
	v_mov_b32_e32 v83, v82
	s_nop 1
	v_permlane32_swap_b32_e32 v82, v83
	v_max_f32_e32 v83, v83, v83
	v_max_f32_e32 v82, v82, v82
	v_max_f32_e32 v82, v82, v83
	v_cmp_ge_f32_e32 vcc, s64, v82
	s_cmp_eq_u64 vcc, exec
	s_cbranch_scc0 .Lgu_b294
	v_mov_b32_e32 v195, 1.0

.Lgu_b292:
	v_add_f32_e32 v114, v114, v115
	v_fmac_f32_e32 v114, v202, v195
	ds_read_b64_tr_b16 v[116:117], v237 offset:0
	ds_read_b64_tr_b16 v[118:119], v237 offset:2048
	ds_read_b64_tr_b16 v[120:121], v237 offset:4096
	ds_read_b64_tr_b16 v[122:123], v237 offset:6144
	ds_read_b64_tr_b16 v[124:125], v237 offset:8192
	ds_read_b64_tr_b16 v[126:127], v237 offset:10240
	ds_read_b64_tr_b16 v[238:239], v237 offset:12288
	ds_read_b64_tr_b16 v[240:241], v237 offset:14336
	s_nop 0
	s_waitcnt lgkmcnt(6)
	v_mfma_f32_32x32x16_bf16 v[2:17], v[110:113], v[116:119], v[2:17]
	ds_read_b64_tr_b16 v[116:117], v237 offset:512
	ds_read_b64_tr_b16 v[118:119], v237 offset:2560
	s_waitcnt lgkmcnt(6)
	v_mfma_f32_32x32x16_bf16 v[2:17], v[106:109], v[120:123], v[2:17]
	ds_read_b64_tr_b16 v[120:121], v237 offset:4608
	ds_read_b64_tr_b16 v[122:123], v237 offset:6656
	s_waitcnt lgkmcnt(6)
	v_mfma_f32_32x32x16_bf16 v[2:17], v[102:105], v[124:127], v[2:17]
	ds_read_b64_tr_b16 v[124:125], v237 offset:8704
	ds_read_b64_tr_b16 v[126:127], v237 offset:10752
	s_waitcnt lgkmcnt(6)
	v_mfma_f32_32x32x16_bf16 v[2:17], v[98:101], v[238:241], v[2:17]
	ds_read_b64_tr_b16 v[238:239], v237 offset:12800
	ds_read_b64_tr_b16 v[240:241], v237 offset:14848
	s_waitcnt lgkmcnt(6)
	v_mfma_f32_32x32x16_bf16 v[18:33], v[110:113], v[116:119], v[18:33]
	ds_read_b64_tr_b16 v[116:117], v237 offset:1024
	ds_read_b64_tr_b16 v[118:119], v237 offset:3072
	s_waitcnt lgkmcnt(6)
	v_mfma_f32_32x32x16_bf16 v[18:33], v[106:109], v[120:123], v[18:33]
	ds_read_b64_tr_b16 v[120:121], v237 offset:5120
	ds_read_b64_tr_b16 v[122:123], v237 offset:7168
	s_waitcnt lgkmcnt(6)
	v_mfma_f32_32x32x16_bf16 v[18:33], v[102:105], v[124:127], v[18:33]
	ds_read_b64_tr_b16 v[124:125], v237 offset:9216
	ds_read_b64_tr_b16 v[126:127], v237 offset:11264
	s_waitcnt lgkmcnt(6)
	v_mfma_f32_32x32x16_bf16 v[18:33], v[98:101], v[238:241], v[18:33]
	ds_read_b64_tr_b16 v[238:239], v237 offset:13312
	ds_read_b64_tr_b16 v[240:241], v237 offset:15360
	s_waitcnt lgkmcnt(6)
	v_mfma_f32_32x32x16_bf16 v[34:49], v[110:113], v[116:119], v[34:49]
	ds_read_b64_tr_b16 v[116:117], v237 offset:1536
	ds_read_b64_tr_b16 v[118:119], v237 offset:3584
	s_waitcnt lgkmcnt(6)
	v_mfma_f32_32x32x16_bf16 v[34:49], v[106:109], v[120:123], v[34:49]
	ds_read_b64_tr_b16 v[120:121], v237 offset:5632
	ds_read_b64_tr_b16 v[122:123], v237 offset:7680
	s_waitcnt lgkmcnt(6)
	v_mfma_f32_32x32x16_bf16 v[34:49], v[102:105], v[124:127], v[34:49]
	ds_read_b64_tr_b16 v[124:125], v237 offset:9728
	ds_read_b64_tr_b16 v[126:127], v237 offset:11776
	s_waitcnt lgkmcnt(6)
	v_mfma_f32_32x32x16_bf16 v[34:49], v[98:101], v[238:241], v[34:49]
	ds_read_b64_tr_b16 v[238:239], v237 offset:13824
	ds_read_b64_tr_b16 v[240:241], v237 offset:15872
	s_waitcnt lgkmcnt(6)
	v_mfma_f32_32x32x16_bf16 v[50:65], v[110:113], v[116:119], v[50:65]
	s_add_i32 s14, s14, 1
	s_cmp_eq_u32 s23, s14
	s_waitcnt lgkmcnt(4)
	v_mfma_f32_32x32x16_bf16 v[50:65], v[106:109], v[120:123], v[50:65]
	s_waitcnt vmcnt(0)
	s_waitcnt lgkmcnt(2)
	v_mfma_f32_32x32x16_bf16 v[50:65], v[102:105], v[124:127], v[50:65]
	s_barrier
	s_waitcnt lgkmcnt(0)
	v_mfma_f32_32x32x16_bf16 v[50:65], v[98:101], v[238:241], v[50:65]
	s_cbranch_scc1 .LBB0_295
	v_mov_b32_e32 v202, v114
	s_branch .Lgu_a286
